# scan stage C hand-rewritten (batched LDS reads, packed f32) in P11 loops + vectorized phase-4 fold, on top of E1 rewrite
# speedup vs baseline: 1.0581x; 1.0213x over previous
.LBB0_490:
	s_or_b64 exec, exec, s[10:11]
	s_load_dword s36, s[0:1], 0x108
	v_cmp_lt_i32_e32 vcc, 3, v10
	s_waitcnt lgkmcnt(0)
	s_cmp_lt_i32 s36, 5
	s_cselect_b64 s[6:7], -1, 0
	s_and_b64 s[8:9], s[6:7], vcc
	v_mov_b32_e32 v0, s36
	s_and_saveexec_b64 s[6:7], s[8:9]
	s_cbranch_execz .LBB0_555
	s_load_dword s14, s[0:1], 0x640
	s_load_dwordx2 s[16:17], s[0:1], 0x100
	s_mov_b64 s[8:9], exec
	v_mov_b32_e32 v1, 0
	v_mov_b32_e32 v177, v1
	v_lshl_add_u32 v2, s2, 8, v176
	v_mov_b32_e32 v22, 1.0
	v_mov_b32_e32 v23, -1.0
	s_waitcnt lgkmcnt(0)
	s_add_u32 s10, s16, 0xd200000
	s_addc_u32 s11, s17, 0
	s_add_u32 s16, s16, 0x6200000
	s_addc_u32 s17, s17, 0
	s_lshl_b32 s15, s14, 8
	s_add_u32 s12, s0, 0x640
	s_addc_u32 s13, s1, 0
.Lp4_loop:
	v_cmp_gt_u32_e32 vcc, 0x80000, v2
	s_and_b64 exec, exec, vcc
	s_cbranch_execz .Lp4_done
	v_lshrrev_b32_e32 v3, 9, v2
	v_and_b32_e32 v4, 0x1ff, v2
	v_lshlrev_b32_e32 v3, 14, v3
	v_lshlrev_b32_e32 v5, 4, v4
	v_cmp_lt_u32_e32 vcc, 0xff, v4
	v_and_b32_e32 v6, 0xff, v4
	v_mov_b32_e32 v7, 0x1000
	v_mov_b32_e32 v8, 0x5000
	v_mov_b32_e32 v25, 0x2000
	v_cndmask_b32_e32 v7, 0, v7, vcc
	v_cndmask_b32_e32 v8, v25, v8, vcc
	v_cndmask_b32_e32 v24, v22, v23, vcc
	v_add3_u32 v9, v3, v5, v7
	v_sub_u32_e32 v8, v8, v5
	v_add_u32_e32 v11, v3, v8
	global_load_dwordx4 v[12:15], v9, s[10:11]
	v_add_u32_e32 v9, -16, v11
	global_load_ushort v20, v11, s[10:11]
	global_load_dwordx4 v[16:19], v9, s[10:11]
	v_add_u32_e32 v9, 0x1000, v3
	global_load_ushort v21, v9, s[10:11]
	v_cmp_eq_u32_e64 s[18:19], 0, v6
	v_cmp_eq_u32_e32 vcc, 0x100, v4
	v_lshlrev_b32_e32 v9, 4, v2
	s_waitcnt vmcnt(0)
	v_lshlrev_b32_e32 v26, 16, v12
	v_and_b32_e32 v27, 0xffff0000, v12
	v_lshlrev_b32_e32 v28, 16, v13
	v_and_b32_e32 v29, 0xffff0000, v13
	v_lshlrev_b32_e32 v30, 16, v14
	v_and_b32_e32 v31, 0xffff0000, v14
	v_lshlrev_b32_e32 v32, 16, v15
	v_and_b32_e32 v33, 0xffff0000, v15
	v_lshlrev_b32_e32 v20, 16, v20
	v_lshlrev_b32_e32 v21, 16, v21
	v_cndmask_b32_e64 v34, v20, 0, s[18:19]
	v_cndmask_b32_e32 v26, v26, v21, vcc
	v_and_b32_e32 v35, 0xffff0000, v19
	v_lshlrev_b32_e32 v36, 16, v19
	v_and_b32_e32 v37, 0xffff0000, v18
	v_lshlrev_b32_e32 v38, 16, v18
	v_and_b32_e32 v39, 0xffff0000, v17
	v_lshlrev_b32_e32 v40, 16, v17
	v_and_b32_e32 v41, 0xffff0000, v16
	v_fmac_f32_e32 v26, v34, v24
	v_fmac_f32_e32 v27, v35, v24
	v_fmac_f32_e32 v28, v36, v24
	v_fmac_f32_e32 v29, v37, v24
	v_fmac_f32_e32 v30, v38, v24
	v_fmac_f32_e32 v31, v39, v24
	v_fmac_f32_e32 v32, v40, v24
	v_fmac_f32_e32 v33, v41, v24
	v_cvt_pk_bf16_f32 v12, v26, v27
	v_cvt_pk_bf16_f32 v13, v28, v29
	v_cvt_pk_bf16_f32 v14, v30, v31
	v_cvt_pk_bf16_f32 v15, v32, v33
	v_add_u32_e32 v2, s15, v2
	global_store_dwordx4 v9, v[12:15], s[16:17]
	s_branch .Lp4_loop
.Lp4_done:
.LBB0_500:
	s_or_b64 exec, exec, s[8:9]
	v_mov_b32_e32 v1, 4
	v_cmp_lt_i32_e32 vcc, 4, v10
	v_mov_b32_e32 v0, s36
	s_and_saveexec_b64 s[8:9], vcc
	s_cbranch_execz .LBB0_554
	s_waitcnt vmcnt(0)
	s_waitcnt lgkmcnt(0)
	s_barrier
	s_and_saveexec_b64 s[10:11], s[4:5]
	s_cbranch_execz .LBB0_553
	v_mov_b32_e32 v0, 0x12000
	s_waitcnt vmcnt(0) expcnt(0) lgkmcnt(0)
	ds_read_b32 v2, v0
	v_mov_b32_e32 v0, 0x12004
	ds_read_b32 v0, v0
	s_waitcnt lgkmcnt(1)
	v_cmp_ne_u32_e32 vcc, 0, v2
	s_cbranch_vccnz .LBB0_517
	s_load_dwordx2 s[18:19], s[12:13], 0x4
	s_add_u32 s12, s22, 0x80200
	s_addc_u32 s13, s23, 0
	s_add_u32 s16, s22, 0x80400
	s_addc_u32 s17, s23, 0
	s_waitcnt lgkmcnt(0)
	s_mul_i32 s3, s18, s14
	s_add_u32 s14, s22, 0x80500
	s_addc_u32 s15, s23, 0
	s_add_u32 s18, s22, 0x80600
	s_mul_i32 s3, s3, s19
	s_addc_u32 s19, s23, 0
	s_add_u32 s20, s22, 0x80700
	s_addc_u32 s21, s23, 0
	s_add_u32 s26, s22, 0x80800
	s_addc_u32 s27, s23, 0
	s_add_u32 s28, s22, 0x80900
	s_addc_u32 s29, s23, 0
	s_add_u32 s30, s22, 0x80a00
	s_addc_u32 s31, s23, 0
	s_add_u32 s34, s22, 0x80b00
	s_addc_u32 s35, s23, 0
	s_add_u32 s36, s22, 0x80c00
	s_addc_u32 s37, s23, 0
	s_add_u32 s38, s22, 0x80d00
	s_addc_u32 s39, s23, 0
	s_add_u32 s40, s22, 0x80e00
	s_addc_u32 s41, s23, 0
	s_add_u32 s42, s22, 0x80f00
	s_addc_u32 s43, s23, 0
	s_add_u32 s44, s22, 0x81000
	s_addc_u32 s45, s23, 0
	s_add_u32 s46, s22, 0x81100
	s_addc_u32 s47, s23, 0
	s_add_u32 s48, s22, 0x81200
	s_addc_u32 s49, s23, 0
	s_add_u32 s50, s22, 0x81300
	s_addc_u32 s51, s23, 0
	s_mov_b32 s58, 1
	v_mov_b32_e32 v16, 0
	s_branch .LBB0_505

.LBB0_1113:
	v_lshlrev_b32_e32 v144, 2, v71
	v_add3_u32 v34, s12, v144, v43
	v_and_b32_e32 v73, 7, v141
	ds_write_b32 v34, v44 offset:7020
	s_waitcnt lgkmcnt(0)
	s_barrier
	s_waitcnt vmcnt(0)
	v_lshrrev_b32_e32 v72, 3, v141
	v_lshlrev_b32_e32 v50, 5, v73
	v_mul_u32_u24_e32 v161, 0x104, v72
	v_cmp_lt_u32_e32 vcc, 0, v72
	v_add_u32_e32 v68, v161, v50
	v_mov_b32_e32 v162, 0x104
	v_add_u32_e32 v69, 0x2080, v68
	ds_read_b128 v[214:217], v50 offset:61120
	ds_read_b128 v[218:221], v50 offset:61136
	ds_read2_b32 v[34:35], v69 offset0:0 offset1:1
	ds_read2_b32 v[36:37], v69 offset0:2 offset1:3
	ds_read2_b32 v[38:39], v69 offset0:4 offset1:5
	ds_read2_b32 v[40:41], v69 offset0:6 offset1:7
	ds_read_b128 v[42:45], v50 offset:61376
	ds_read_b128 v[46:49], v50 offset:61392
	ds_read2_b32 v[60:61], v68 offset0:0 offset1:1
	ds_read2_b32 v[62:63], v68 offset0:2 offset1:3
	ds_read2_b32 v[64:65], v68 offset0:4 offset1:5
	ds_read2_b32 v[66:67], v68 offset0:6 offset1:7
	v_mov_b32_e32 v230, 0x3fb8aa3b
	v_mov_b32_e32 v231, 0x3fb8aa3b
	v_cndmask_b32_e32 v162, 0, v162, vcc
	v_cndmask_b32_e32 v143, 0, v230, vcc
	v_mov_b32_e32 v232, 1.0
	v_mov_b32_e32 v233, 1.0
	v_sub_u32_e32 v145, v68, v162
	v_add_u32_e32 v158, 0x1f7c, v50
	v_mul_u32_u24_e32 v159, 0x280, v73
	v_lshrrev_b32_e32 v161, 3, v72
	v_and_b32_e32 v163, 4, v73
	v_xor_b32_e32 v161, v161, v73
	v_lshl_add_u32 v159, v163, 4, v159
	v_and_b32_e32 v161, 3, v161
	v_and_b32_e32 v163, 7, v72
	v_lshl_add_u32 v159, v161, 4, v159
	v_mul_u32_u24_e32 v160, 0x90, v72
	v_lshl_add_u32 v159, v163, 1, v159
	v_lshl_add_u32 v160, v73, 4, v160
	v_lshlrev_b32_e32 v222, 16, v122
	v_and_b32_e32 v223, 0xffff0000, v122
	v_lshlrev_b32_e32 v224, 16, v123
	v_and_b32_e32 v225, 0xffff0000, v123
	v_lshlrev_b32_e32 v226, 16, v124
	v_and_b32_e32 v227, 0xffff0000, v124
	v_lshlrev_b32_e32 v228, 16, v125
	v_and_b32_e32 v229, 0xffff0000, v125
	s_waitcnt lgkmcnt(0)
	ds_read2_b32 v[74:75], v158 offset0:0 offset1:1
	ds_read2_b32 v[76:77], v158 offset0:2 offset1:3
	ds_read2_b32 v[78:79], v158 offset0:4 offset1:5
	ds_read2_b32 v[80:81], v158 offset0:6 offset1:7
	ds_read2_b32 v[126:127], v145 offset0:0 offset1:1
	ds_read2_b32 v[128:129], v145 offset0:2 offset1:3
	ds_read2_b32 v[130:131], v145 offset0:4 offset1:5
	ds_read2_b32 v[132:133], v145 offset0:6 offset1:7
	v_pk_mul_f32 v[214:215], v[214:215], v[222:223]
	v_pk_mul_f32 v[216:217], v[216:217], v[224:225]
	v_pk_mul_f32 v[218:219], v[218:219], v[226:227]
	v_pk_mul_f32 v[220:221], v[220:221], v[228:229]
	v_pk_mul_f32 v[234:235], v[214:215], v[214:215]
	v_pk_fma_f32 v[234:235], v[216:217], v[216:217], v[234:235]
	v_pk_fma_f32 v[234:235], v[218:219], v[218:219], v[234:235]
	v_pk_fma_f32 v[234:235], v[220:221], v[220:221], v[234:235]
	v_pk_add_f32 v[52:53], v[34:35], v[232:233] neg_lo:[0,1] neg_hi:[0,1]
	v_pk_add_f32 v[54:55], v[36:37], v[232:233] neg_lo:[0,1] neg_hi:[0,1]
	v_pk_add_f32 v[56:57], v[38:39], v[232:233] neg_lo:[0,1] neg_hi:[0,1]
	v_pk_add_f32 v[58:59], v[40:41], v[232:233] neg_lo:[0,1] neg_hi:[0,1]
	v_add_f32_e32 v234, v234, v235
	v_pk_fma_f32 v[42:43], v[52:53], v[42:43], v[232:233]
	v_pk_fma_f32 v[44:45], v[54:55], v[44:45], v[232:233]
	v_add_f32_dpp v234, v234, v234 quad_perm:[1,0,3,2] row_mask:0xf bank_mask:0xf bound_ctrl:1
	v_pk_fma_f32 v[46:47], v[56:57], v[46:47], v[232:233]
	v_pk_fma_f32 v[48:49], v[58:59], v[48:49], v[232:233]
	v_add_f32_dpp v234, v234, v234 quad_perm:[2,3,0,1] row_mask:0xf bank_mask:0xf bound_ctrl:1
	v_pk_mul_f32 v[222:223], v[222:223], v[42:43]
	v_pk_mul_f32 v[224:225], v[224:225], v[44:45]
	v_mov_b32_dpp v235, v234 row_half_mirror row_mask:0xf bank_mask:0xf bound_ctrl:1
	v_pk_mul_f32 v[226:227], v[226:227], v[46:47]
	v_pk_mul_f32 v[228:229], v[228:229], v[48:49]
	ds_read_b128 v[42:45], v50 offset:61632
	ds_read_b128 v[46:49], v50 offset:61648
	v_add_f32_e32 v234, v234, v235
	v_add_f32_e32 v234, 0x2b8cbccc, v234
	v_rsq_f32_e32 v234, v234
	s_waitcnt lgkmcnt(2)
	v_pk_mul_f32 v[214:215], v[214:215], v[234:235] op_sel_hi:[1,0]
	v_pk_mul_f32 v[216:217], v[216:217], v[234:235] op_sel_hi:[1,0]
	v_pk_mul_f32 v[218:219], v[218:219], v[234:235] op_sel_hi:[1,0]
	v_pk_mul_f32 v[220:221], v[220:221], v[234:235] op_sel_hi:[1,0]
	v_cmp_eq_u32_e32 vcc, 31, v72
	v_pk_mul_f32 v[52:53], v[214:215], v[34:35]
	v_pk_mul_f32 v[54:55], v[216:217], v[36:37]
	v_pk_mul_f32 v[56:57], v[218:219], v[38:39]
	v_pk_mul_f32 v[58:59], v[220:221], v[40:41]
	s_and_saveexec_b64 s[60:61], vcc
	s_cbranch_execz .Lc_nogc_b
	v_pk_mul_f32 v[34:35], v[74:75], v[230:231]
	v_pk_mul_f32 v[36:37], v[76:77], v[230:231]
	v_pk_mul_f32 v[38:39], v[78:79], v[230:231]
	v_pk_mul_f32 v[40:41], v[80:81], v[230:231]
	v_exp_f32_e64 v34, v34
	v_exp_f32_e64 v35, v35
	v_exp_f32_e64 v36, v36
	v_exp_f32_e64 v37, v37
	v_exp_f32_e64 v38, v38
	v_exp_f32_e64 v39, v39
	v_exp_f32_e64 v40, v40
	v_exp_f32_e64 v41, v41
	ds_write_b128 v50, v[34:37] offset:60864
	ds_write_b128 v50, v[38:41] offset:60880
.Lc_nogc_b:
	s_or_b64 exec, exec, s[60:61]
	v_pk_add_f32 v[74:75], v[74:75], v[60:61] neg_lo:[0,1] neg_hi:[0,1]
	v_pk_add_f32 v[76:77], v[76:77], v[62:63] neg_lo:[0,1] neg_hi:[0,1]
	v_pk_add_f32 v[78:79], v[78:79], v[64:65] neg_lo:[0,1] neg_hi:[0,1]
	v_pk_add_f32 v[80:81], v[80:81], v[66:67] neg_lo:[0,1] neg_hi:[0,1]
	v_pk_mul_f32 v[74:75], v[74:75], v[230:231]
	v_pk_mul_f32 v[76:77], v[76:77], v[230:231]
	v_pk_mul_f32 v[78:79], v[78:79], v[230:231]
	v_pk_mul_f32 v[80:81], v[80:81], v[230:231]
	v_pk_mul_f32 v[60:61], v[60:61], v[230:231]
	v_pk_mul_f32 v[62:63], v[62:63], v[230:231]
	v_pk_mul_f32 v[64:65], v[64:65], v[230:231]
	v_pk_mul_f32 v[66:67], v[66:67], v[230:231]
	v_exp_f32_e64 v74, v74
	v_exp_f32_e64 v75, v75
	v_exp_f32_e64 v76, v76
	v_exp_f32_e64 v77, v77
	v_exp_f32_e64 v78, v78
	v_exp_f32_e64 v79, v79
	v_exp_f32_e64 v80, v80
	v_exp_f32_e64 v81, v81
	v_mul_f32_e32 v126, v143, v126
	v_mul_f32_e32 v127, v143, v127
	v_mul_f32_e32 v128, v143, v128
	v_mul_f32_e32 v129, v143, v129
	v_mul_f32_e32 v130, v143, v130
	v_mul_f32_e32 v131, v143, v131
	v_mul_f32_e32 v132, v143, v132
	v_mul_f32_e32 v133, v143, v133
	v_pk_mul_f32 v[34:35], v[52:53], v[74:75]
	v_pk_mul_f32 v[36:37], v[54:55], v[76:77]
	v_pk_mul_f32 v[38:39], v[56:57], v[78:79]
	v_pk_mul_f32 v[40:41], v[58:59], v[80:81]
	v_pk_mul_f32 v[74:75], v[222:223], v[74:75]
	v_pk_mul_f32 v[76:77], v[224:225], v[76:77]
	v_pk_mul_f32 v[78:79], v[226:227], v[78:79]
	v_pk_mul_f32 v[80:81], v[228:229], v[80:81]
	v_cvt_pk_bf16_f32 v34, v34, v35
	v_cvt_pk_bf16_f32 v35, v36, v37
	v_cvt_pk_bf16_f32 v36, v38, v39
	v_cvt_pk_bf16_f32 v37, v40, v41
	v_cvt_pk_bf16_f32 v38, v74, v75
	v_cvt_pk_bf16_f32 v39, v76, v77
	v_cvt_pk_bf16_f32 v40, v78, v79
	v_cvt_pk_bf16_f32 v41, v80, v81
	ds_write_b16 v159, v34 offset:35072
	ds_write_b16_d16_hi v159, v34 offset:35152
	ds_write_b16 v159, v35 offset:35232
	ds_write_b16_d16_hi v159, v35 offset:35312
	ds_write_b16 v159, v36 offset:35392
	ds_write_b16_d16_hi v159, v36 offset:35472
	ds_write_b16 v159, v37 offset:35552
	ds_write_b16_d16_hi v159, v37 offset:35632
	v_exp_f32_e64 v126, v126
	v_exp_f32_e64 v127, v127
	v_exp_f32_e64 v128, v128
	v_exp_f32_e64 v129, v129
	v_exp_f32_e64 v130, v130
	v_exp_f32_e64 v131, v131
	v_exp_f32_e64 v132, v132
	v_exp_f32_e64 v133, v133
	ds_write_b16 v159, v38 offset:40256
	s_waitcnt lgkmcnt(5)
	ds_write_b16_d16_hi v159, v38 offset:40336
	ds_write_b16 v159, v39 offset:40416
	ds_write_b16_d16_hi v159, v39 offset:40496
	ds_write_b16 v159, v40 offset:40576
	ds_write_b16_d16_hi v159, v40 offset:40656
	ds_write_b16 v159, v41 offset:40736
	ds_write_b16_d16_hi v159, v41 offset:40816
	ds_write_b16 v159, v118 offset:45440
	s_waitcnt lgkmcnt(5)
	ds_write_b16_d16_hi v159, v118 offset:45520
	ds_write_b16 v159, v119 offset:45600
	ds_write_b16_d16_hi v159, v119 offset:45680
	ds_write_b16 v159, v120 offset:45760
	ds_write_b16_d16_hi v159, v120 offset:45840
	ds_write_b16 v159, v121 offset:45920
	ds_write_b16_d16_hi v159, v121 offset:46000
	v_pk_mul_f32 v[126:127], v[214:215], v[126:127] neg_lo:[1,0] neg_hi:[1,0]
	v_pk_mul_f32 v[128:129], v[216:217], v[128:129] neg_lo:[1,0] neg_hi:[1,0]
	v_pk_mul_f32 v[130:131], v[218:219], v[130:131] neg_lo:[1,0] neg_hi:[1,0]
	v_pk_mul_f32 v[132:133], v[220:221], v[132:133] neg_lo:[1,0] neg_hi:[1,0]
	v_exp_f32_e64 v74, -v60
	v_exp_f32_e64 v75, -v61
	v_exp_f32_e64 v76, -v62
	v_exp_f32_e64 v77, -v63
	v_exp_f32_e64 v78, -v64
	v_exp_f32_e64 v79, -v65
	v_exp_f32_e64 v80, -v66
	v_exp_f32_e64 v81, -v67
	v_cvt_pk_bf16_f32 v126, v126, v127
	v_cvt_pk_bf16_f32 v127, v128, v129
	v_cvt_pk_bf16_f32 v128, v130, v131
	v_cvt_pk_bf16_f32 v129, v132, v133
	s_waitcnt lgkmcnt(8)
	ds_write_b128 v160, v[126:129] offset:16640
	v_exp_f32_e64 v60, v60
	v_exp_f32_e64 v61, v61
	v_exp_f32_e64 v62, v62
	v_exp_f32_e64 v63, v63
	v_exp_f32_e64 v64, v64
	v_exp_f32_e64 v65, v65
	v_exp_f32_e64 v66, v66
	v_exp_f32_e64 v67, v67
	v_lshlrev_b32_e32 v34, 16, v114
	v_and_b32_e32 v35, 0xffff0000, v114
	v_lshlrev_b32_e32 v36, 16, v115
	v_and_b32_e32 v37, 0xffff0000, v115
	v_lshlrev_b32_e32 v38, 16, v116
	v_and_b32_e32 v39, 0xffff0000, v116
	v_lshlrev_b32_e32 v40, 16, v117
	v_and_b32_e32 v41, 0xffff0000, v117
	v_pk_mul_f32 v[42:43], v[42:43], v[34:35]
	v_pk_mul_f32 v[44:45], v[44:45], v[36:37]
	v_pk_mul_f32 v[46:47], v[46:47], v[38:39]
	v_pk_mul_f32 v[48:49], v[48:49], v[40:41]
	v_pk_mul_f32 v[34:35], v[34:35], v[60:61]
	v_pk_mul_f32 v[36:37], v[36:37], v[62:63]
	v_pk_mul_f32 v[38:39], v[38:39], v[64:65]
	v_pk_mul_f32 v[40:41], v[40:41], v[66:67]
	v_pk_mul_f32 v[234:235], v[42:43], v[222:223]
	v_pk_fma_f32 v[234:235], v[44:45], v[224:225], v[234:235]
	v_pk_fma_f32 v[234:235], v[46:47], v[226:227], v[234:235]
	v_pk_fma_f32 v[234:235], v[48:49], v[228:229], v[234:235]
	v_cvt_pk_bf16_f32 v34, v34, v35
	v_cvt_pk_bf16_f32 v35, v36, v37
	v_cvt_pk_bf16_f32 v36, v38, v39
	v_cvt_pk_bf16_f32 v37, v40, v41
	ds_write_b128 v160, v[34:37] offset:21248
	v_pk_mul_f32 v[52:53], v[52:53], v[74:75]
	v_pk_mul_f32 v[54:55], v[54:55], v[76:77]
	v_pk_mul_f32 v[56:57], v[56:57], v[78:79]
	v_pk_mul_f32 v[58:59], v[58:59], v[80:81]
	v_pk_mul_f32 v[222:223], v[222:223], v[74:75]
	v_pk_mul_f32 v[224:225], v[224:225], v[76:77]
	v_pk_mul_f32 v[226:227], v[226:227], v[78:79]
	v_pk_mul_f32 v[228:229], v[228:229], v[80:81]
	v_cvt_pk_bf16_f32 v52, v52, v53
	v_cvt_pk_bf16_f32 v53, v54, v55
	v_cvt_pk_bf16_f32 v54, v56, v57
	v_cvt_pk_bf16_f32 v55, v58, v59
	v_cvt_pk_bf16_f32 v222, v222, v223
	v_cvt_pk_bf16_f32 v223, v224, v225
	v_cvt_pk_bf16_f32 v224, v226, v227
	v_cvt_pk_bf16_f32 v225, v228, v229
	s_waitcnt lgkmcnt(8)
	ds_write_b128 v160, v[52:55] offset:25856
	ds_write_b128 v160, v[222:225] offset:30464
	v_lshlrev_b32_e32 v57, 3, v73
	v_add_f32_e32 v38, v234, v235
	s_nop 1
	v_add_f32_dpp v34, v38, v38 quad_perm:[1,0,3,2] row_mask:0xf bank_mask:0xf bound_ctrl:1
	v_cmp_eq_u32_e32 vcc, 0, v73
	s_nop 0
	v_add_f32_dpp v34, v34, v34 quad_perm:[2,3,0,1] row_mask:0xf bank_mask:0xf bound_ctrl:1
	s_nop 1
	v_mov_b32_dpp v35, v34 row_half_mirror row_mask:0xf bank_mask:0xf bound_ctrl:1
	s_and_saveexec_b64 s[12:13], vcc
	s_cbranch_execz .LBB0_1147
	v_add_f32_e32 v34, v34, v35
	v_ashrrev_i32_e32 v143, 31, v142
	v_mul_f32_e32 v36, 0.5, v34
	v_lshlrev_b64 v[34:35], 6, v[142:143]
	v_lshl_add_u64 v[34:35], s[52:53], 0, v[34:35]
	global_atomic_add_f32 v[34:35], v36, off
